# plus windowed loop: packed f32 ops split into scalar ops
# baseline (speedup 1.0000x reference)
; #define LAS __attribute__((address_space(3)))
; __device__ __forceinline__ void attn_win(LAS unsigned char* lds, const bf16_t* __restrict__ PROJ, const bf16_t* __restrict__ VT, bf16_t* __restrict__ AO, ...
;     ...
;         const int k0 = t * 64;
;         if ((k0 + 63 >= qw - 128) && (k0 <= qw + 31 + 128)) {
;             const LAS unsigned char* kb = lds + OFF_K + cur * TB + r32 * KP + hi * 16;
;             f32x16 sA = {}, sB = {};
; #pragma unroll
;             for (int ds = 0; ds < 4; ++ds) {
;                 const bf16x8 ka = *(const LAS bf16x8*)(kb + ds * 32);
;                 const bf16x8 kb2 = *(const LAS bf16x8*)(kb + 32 * KP + ds * 32);
;                 sA = __builtin_amdgcn_mfma_f32_32x32x16_bf16(ka, qf[ds], sA, 0, 0, 0);
;                 sB = __builtin_amdgcn_mfma_f32_32x32x16_bf16(kb2, qf[ds], sB, 0, 0, 0);
;             }
;             { const LAS float* lp = lut + (k0 - (qw + r32) + 224 + 4 * hi);
; #pragma unroll
;               for (int r = 0; r < 16; ++r) { sA[r] += lp[(r & 3) + 8 * (r >> 2)]; sB[r] += lp[32 + (r & 3) + 8 * (r >> 2)]; } }
;             float mx0 = fmaxf(sA[0], sB[0]), mx1 = fmaxf(sA[1], sB[1]), mx2 = fmaxf(sA[2], sB[2]), mx3 = fmaxf(sA[3], sB[3]);
; #pragma unroll
;             for (int r = 4; r < 16; r += 4) { mx0 = fmaxf(mx0, fmaxf(sA[r], sB[r])); mx1 = fmaxf(mx1, fmaxf(sA[r + 1], sB[r + 1])); mx2 = fmaxf(mx2, fmaxf(sA[r + 2], sB[r + 2])); mx3 = fmaxf(mx3, fmaxf(sA[r + 3], sB[r + 3])); }
;             float mx = fmaxf(fmaxf(mx0, mx1), fmaxf(mx2, mx3));
;             mx = fmaxf(mx, __shfl_xor(mx, 32));
.LBB0_268:
	s_add_i32 s30, s10, 63
	s_cmp_lt_i32 s30, s11
	s_cselect_b64 s[30:31], -1, 0
	s_cmp_gt_u32 s10, s12
	s_cselect_b64 s[64:65], -1, 0
	s_or_b64 s[30:31], s[30:31], s[64:65]
	s_and_b64 vcc, exec, s[30:31]
	s_cbranch_vccnz .LBB0_264
	s_mulk_i32 s14, 0x2400
	v_add_u32_e32 v97, s14, v95
	ds_read_b128 v[48:51], v97 offset:4608
	s_waitcnt lgkmcnt(3)
	ds_read_b128 v[32:35], v97
	ds_read_b128 v[100:103], v97 offset:32
	ds_read_b128 v[104:107], v97 offset:4640
	s_waitcnt lgkmcnt(3)
	v_mfma_f32_32x32x16_bf16 v[48:63], v[48:51], v[64:67], 0
	s_waitcnt lgkmcnt(2)
	v_mfma_f32_32x32x16_bf16 v[32:47], v[32:35], v[64:67], 0
	s_waitcnt lgkmcnt(1)
	v_mfma_f32_32x32x16_bf16 v[32:47], v[100:103], v[68:71], v[32:47]
	s_waitcnt lgkmcnt(0)
	v_mfma_f32_32x32x16_bf16 v[48:63], v[104:107], v[68:71], v[48:63]
	ds_read_b128 v[100:103], v97 offset:64
	ds_read_b128 v[104:107], v97 offset:4672
	s_waitcnt vmcnt(1) lgkmcnt(1)
	v_mfma_f32_32x32x16_bf16 v[32:47], v[100:103], v[72:75], v[32:47]
	s_waitcnt lgkmcnt(0)
	v_mfma_f32_32x32x16_bf16 v[48:63], v[104:107], v[72:75], v[48:63]
	ds_read_b128 v[100:103], v97 offset:96
	ds_read_b128 v[104:107], v97 offset:4704
	s_waitcnt vmcnt(0) lgkmcnt(1)
	v_mfma_f32_32x32x16_bf16 v[32:47], v[100:103], v[80:83], v[32:47]
	ds_read2_b32 v[100:101], v96 offset1:1
	ds_read2_b32 v[102:103], v96 offset0:32 offset1:33
	s_waitcnt lgkmcnt(2)
	v_mfma_f32_32x32x16_bf16 v[48:63], v[104:107], v[80:83], v[48:63]
	s_waitcnt lgkmcnt(1)
	s_nop 6
	v_add_f32_e32 v99, v32, v100
	v_add_f32_e32 v101, v33, v101
	ds_read2_b32 v[32:33], v96 offset0:2 offset1:3
	s_waitcnt lgkmcnt(1)
	v_add_f32_e32 v100, v48, v102
	v_add_f32_e32 v102, v49, v103
	ds_read2_b32 v[48:49], v96 offset0:34 offset1:35
	s_waitcnt lgkmcnt(1)
	v_add_f32_e32 v103, v34, v32
	s_waitcnt lgkmcnt(0)
	v_add_f32_e32 v48, v50, v48
	v_add_f32_e32 v50, v35, v33
	ds_read2_b32 v[32:33], v96 offset0:8 offset1:9
	ds_read2_b32 v[34:35], v96 offset0:40 offset1:41
	v_add_f32_e32 v49, v51, v49
	s_waitcnt lgkmcnt(1)
	v_add_f32_e32 v51, v36, v32
	s_waitcnt lgkmcnt(0)
	v_add_f32_e32 v52, v52, v34
	v_add_f32_e32 v104, v37, v33
	v_add_f32_e32 v53, v53, v35
	ds_read2_b32 v[32:33], v96 offset0:10 offset1:11
	ds_read2_b32 v[34:35], v96 offset0:42 offset1:43
	s_waitcnt lgkmcnt(1)
	v_add_f32_e32 v105, v38, v32
	s_waitcnt lgkmcnt(0)
	v_add_f32_e32 v54, v54, v34
	v_add_f32_e32 v106, v39, v33
	v_add_f32_e32 v55, v55, v35
	ds_read2_b32 v[32:33], v96 offset0:16 offset1:17
	ds_read2_b32 v[34:35], v96 offset0:48 offset1:49
	v_max_f32_e32 v36, v106, v55
	v_max3_f32 v36, v50, v49, v36
	s_waitcnt lgkmcnt(1)
	v_add_f32_e32 v107, v40, v32
	s_waitcnt lgkmcnt(0)
	v_add_f32_e32 v108, v56, v34
	v_add_f32_e32 v109, v41, v33
	v_add_f32_e32 v57, v57, v35
	ds_read2_b32 v[32:33], v96 offset0:18 offset1:19
	ds_read2_b32 v[34:35], v96 offset0:50 offset1:51
	v_max_f32_e32 v37, v107, v108
	v_max_f32_e32 v38, v109, v57
	s_waitcnt lgkmcnt(1)
	v_add_f32_e32 v110, v42, v32
	s_waitcnt lgkmcnt(0)
	v_add_f32_e32 v111, v58, v34
	v_add_f32_e32 v112, v43, v33
	v_add_f32_e32 v113, v59, v35
	ds_read2_b32 v[32:33], v96 offset0:24 offset1:25
	ds_read2_b32 v[34:35], v96 offset0:56 offset1:57
	v_max_f32_e32 v39, v110, v111
	s_waitcnt lgkmcnt(1)
	v_add_f32_e32 v44, v44, v32
	s_waitcnt lgkmcnt(0)
	v_add_f32_e32 v114, v60, v34
	v_add_f32_e32 v115, v45, v33
	v_add_f32_e32 v116, v61, v35
	ds_read2_b32 v[32:33], v96 offset0:26 offset1:27
	ds_read2_b32 v[34:35], v96 offset0:58 offset1:59
	s_waitcnt lgkmcnt(1)
	v_add_f32_e32 v117, v46, v32
	v_add_f32_e32 v119, v47, v33
	s_waitcnt lgkmcnt(0)
	v_add_f32_e32 v120, v63, v35
	v_max_f32_e32 v32, v103, v48
	v_max_f32_e32 v33, v51, v52
	v_max_f32_e32 v35, v105, v54
	v_add_f32_e32 v118, v62, v34
	v_max3_f32 v33, v99, v100, v33
	v_max_f32_e32 v34, v104, v53
	v_max3_f32 v32, v32, v35, v39
	v_max_f32_e32 v39, v44, v114
	v_max3_f32 v34, v101, v102, v34
	v_max3_f32 v33, v33, v37, v39
	v_max_f32_e32 v37, v115, v116
	v_max_f32_e32 v35, v112, v113
	v_max3_f32 v34, v34, v38, v37
	v_max_f32_e32 v38, v119, v120
	v_max_f32_e32 v37, v117, v118
	v_max3_f32 v35, v36, v35, v38
	v_max3_f32 v32, v32, v37, v35
	v_max3_f32 v32, v33, v34, v32
	ds_bpermute_b32 v33, v166, v32
	s_waitcnt lgkmcnt(0)
; #define LAS __attribute__((address_space(3)))
; __device__ __forceinline__ unsigned cvtpk(float lo, float hi) { f32x2_t v = {lo, hi}; bf16x2_t b = __builtin_convertvector(v, bf16x2_t); return __builtin_bit_cast(unsigned, b); }
; __device__ __forceinline__ void attn_win(LAS unsigned char* lds, const bf16_t* __restrict__ PROJ, const bf16_t* __restrict__ VT, bf16_t* __restrict__ AO, ...
;     ...
;             const float mn = fmaxf(m, mx);
;             const float alpha = __builtin_amdgcn_exp2f(m - mn);
;             m = mn;
;             float ps0 = 0.f, ps1 = 0.f, ps2 = 0.f, ps3 = 0.f;
; #pragma unroll
;             for (int r = 0; r < 16; r += 4) {
; #pragma unroll
;                 for (int q = 0; q < 4; ++q) { sA[r + q] = __builtin_amdgcn_exp2f(sA[r + q] - mn); sB[r + q] = __builtin_amdgcn_exp2f(sB[r + q] - mn); }
;                 ps0 += sA[r] + sB[r]; ps1 += sA[r + 1] + sB[r + 1]; ps2 += sA[r + 2] + sB[r + 2]; ps3 += sA[r + 3] + sB[r + 3]; }
;             l = l * alpha + ((ps0 + ps1) + (ps2 + ps3));
; #pragma unroll
;             for (int r = 0; r < 16; ++r) { o0[r] *= alpha; o1[r] *= alpha; }
;             bf16x8 pk[4];
;             { u32x4 w;
;               w.x = cvtpk(sA[0], sA[1]); w.y = cvtpk(sA[2], sA[3]); w.z = cvtpk(sA[4], sA[5]); w.w = cvtpk(sA[6], sA[7]); pk[0] = __builtin_bit_cast(bf16x8, w);
;               w.x = cvtpk(sA[8], sA[9]); w.y = cvtpk(sA[10], sA[11]); w.z = cvtpk(sA[12], sA[13]); w.w = cvtpk(sA[14], sA[15]); pk[1] = __builtin_bit_cast(bf16x8, w);
;               w.x = cvtpk(sB[0], sB[1]); w.y = cvtpk(sB[2], sB[3]); w.z = cvtpk(sB[4], sB[5]); w.w = cvtpk(sB[6], sB[7]); pk[2] = __builtin_bit_cast(bf16x8, w);
;               w.x = cvtpk(sB[8], sB[9]); w.y = cvtpk(sB[10], sB[11]); w.z = cvtpk(sB[12], sB[13]); w.w = cvtpk(sB[14], sB[15]); pk[3] = __builtin_bit_cast(bf16x8, w); }
;             const LAS unsigned char* vb = lds + OFF_V + cur * TB + r32 * KP + hi * 16;
; #pragma unroll
;             for (int s = 0; s < 4; ++s) {
;                 const bf16x8 va = *(const LAS bf16x8*)(vb + s * 32);
;                 const bf16x8 vb2 = *(const LAS bf16x8*)(vb + 32 * KP + s * 32);
;                 o0 = __builtin_amdgcn_mfma_f32_32x32x16_bf16(va, pk[s], o0, 0, 0, 0);
;                 o1 = __builtin_amdgcn_mfma_f32_32x32x16_bf16(vb2, pk[s], o1, 0, 0, 0);
;             }
	v_max3_f32 v45, v98, v32, v33
	v_sub_f32_e32 v33, v101, v45
	v_sub_f32_e32 v35, v50, v45
	v_sub_f32_e32 v50, v107, v45
	v_exp_f32_e32 v38, v33
	v_sub_f32_e32 v33, v102, v45
	v_sub_f32_e32 v41, v52, v45
	v_exp_f32_e32 v56, v50
	v_sub_f32_e32 v50, v108, v45
	v_sub_f32_e32 v32, v99, v45
	v_exp_f32_e32 v34, v33
	v_sub_f32_e32 v33, v103, v45
	v_exp_f32_e32 v46, v41
	v_sub_f32_e32 v41, v104, v45
	v_exp_f32_e32 v58, v50
	v_sub_f32_e32 v50, v109, v45
	v_sub_f32_e32 v44, v44, v45
	v_sub_f32_e32 v121, v98, v45
	v_exp_f32_e32 v36, v32
	v_sub_f32_e32 v32, v100, v45
	v_exp_f32_e32 v37, v33
	v_sub_f32_e32 v33, v48, v45
	v_exp_f32_e32 v42, v41
	v_sub_f32_e32 v41, v53, v45
	v_exp_f32_e32 v60, v50
	v_sub_f32_e32 v50, v57, v45
	v_exp_f32_e32 v98, v44
	v_sub_f32_e32 v44, v114, v45
	v_exp_f32_e32 v32, v32
	v_exp_f32_e32 v33, v33
	v_exp_f32_e32 v39, v35
	v_sub_f32_e32 v35, v49, v45
	v_sub_f32_e32 v40, v51, v45
	v_exp_f32_e32 v48, v41
	v_sub_f32_e32 v41, v105, v45
	v_sub_f32_e32 v43, v54, v45
	v_exp_f32_e32 v62, v50
	v_sub_f32_e32 v50, v110, v45
	v_exp_f32_e32 v100, v44
	v_sub_f32_e32 v44, v115, v45
	v_exp_f32_e32 v35, v35
	v_exp_f32_e32 v40, v40
	v_exp_f32_e32 v41, v41
	v_exp_f32_e32 v47, v43
	v_sub_f32_e32 v43, v106, v45
	v_sub_f32_e32 v49, v55, v45
	v_exp_f32_e32 v57, v50
	v_sub_f32_e32 v50, v111, v45
	v_exp_f32_e32 v102, v44
	v_sub_f32_e32 v44, v116, v45
	v_exp_f32_e32 v43, v43
	v_exp_f32_e32 v49, v49
	v_exp_f32_e32 v59, v50
	v_sub_f32_e32 v50, v112, v45
	v_exp_f32_e32 v104, v44
	v_sub_f32_e32 v44, v117, v45
	v_exp_f32_e32 v61, v50
	v_sub_f32_e32 v50, v113, v45
	v_exp_f32_e32 v99, v44
	v_sub_f32_e32 v44, v118, v45
	v_exp_f32_e32 v63, v50
	v_exp_f32_e32 v101, v44
	v_sub_f32_e32 v44, v119, v45
	v_add_f32_e32 v50, v32, v36
	v_add_f32_e32 v51, v33, v37
	v_exp_f32_e32 v103, v44
	v_sub_f32_e32 v44, v120, v45
	v_add_f32_e32 v52, v34, v38
	v_add_f32_e32 v53, v35, v39
	v_add_f32_e32 v54, v46, v40
	v_add_f32_e32 v55, v47, v41
	v_exp_f32_e32 v105, v44
	v_add_f32_e32 v50, v54, v50
	v_add_f32_e32 v51, v55, v51
	v_add_f32_e32 v54, v48, v42
	v_add_f32_e32 v55, v49, v43
	v_exp_f32_e32 v44, v121
	v_add_f32_e32 v52, v54, v52
	v_add_f32_e32 v53, v55, v53
	v_add_f32_e32 v54, v58, v56
	v_add_f32_e32 v55, v59, v57
	v_mul_f32_e32 v14, v14, v44
	v_mul_f32_e32 v15, v15, v44
	v_add_f32_e32 v50, v54, v50
	v_add_f32_e32 v51, v55, v51
	v_add_f32_e32 v54, v62, v60
	v_add_f32_e32 v55, v63, v61
	v_mul_f32_e32 v12, v12, v44
	v_mul_f32_e32 v13, v13, v44
	v_add_f32_e32 v52, v54, v52
	v_add_f32_e32 v53, v55, v53
	v_add_f32_e32 v54, v100, v98
	v_add_f32_e32 v55, v101, v99
	v_mul_f32_e32 v10, v10, v44
	v_mul_f32_e32 v11, v11, v44
	v_add_f32_e32 v50, v54, v50
	v_add_f32_e32 v51, v55, v51
	v_add_f32_e32 v54, v104, v102
	v_add_f32_e32 v55, v105, v103
	v_mul_f32_e32 v8, v8, v44
	v_mul_f32_e32 v9, v9, v44
	v_add_f32_e32 v52, v54, v52
	v_add_f32_e32 v53, v55, v53
	v_cvt_pk_bf16_f32 v54, v40, v42
	v_add_f32_e32 v50, v50, v52
	v_add_f32_e32 v51, v51, v53
	v_cvt_pk_bf16_f32 v52, v36, v38
	v_cvt_pk_bf16_f32 v53, v37, v39
	v_cvt_pk_bf16_f32 v55, v41, v43
	v_cvt_pk_bf16_f32 v40, v56, v60
	v_cvt_pk_bf16_f32 v41, v57, v61
	v_cvt_pk_bf16_f32 v36, v32, v34
	v_cvt_pk_bf16_f32 v37, v33, v35
	v_cvt_pk_bf16_f32 v38, v46, v48
	v_cvt_pk_bf16_f32 v39, v47, v49
	v_cvt_pk_bf16_f32 v32, v58, v62
	v_cvt_pk_bf16_f32 v33, v59, v63
	ds_read_b128 v[46:49], v97 offset:18432
	ds_read_b128 v[56:59], v97 offset:23040
	v_mul_f32_e32 v6, v6, v44
	v_mul_f32_e32 v7, v7, v44
	v_mul_f32_e32 v4, v4, v44
	v_mul_f32_e32 v5, v5, v44
	v_mul_f32_e32 v2, v2, v44
	v_mul_f32_e32 v3, v3, v44
	v_mul_f32_e32 v0, v0, v44
	v_mul_f32_e32 v1, v1, v44
	v_mul_f32_e32 v30, v30, v44
	v_mul_f32_e32 v31, v31, v44
	v_mul_f32_e32 v28, v28, v44
	v_mul_f32_e32 v29, v29, v44
	v_mul_f32_e32 v26, v26, v44
	v_mul_f32_e32 v27, v27, v44
	v_mul_f32_e32 v24, v24, v44
	v_mul_f32_e32 v25, v25, v44
	v_mul_f32_e32 v22, v22, v44
	v_mul_f32_e32 v23, v23, v44
	v_mul_f32_e32 v20, v20, v44
	v_mul_f32_e32 v21, v21, v44
	v_mul_f32_e32 v18, v18, v44
	v_mul_f32_e32 v19, v19, v44
	v_mul_f32_e32 v16, v16, v44
	v_mul_f32_e32 v17, v17, v44
	s_waitcnt lgkmcnt(1)
	v_mfma_f32_32x32x16_bf16 v[0:15], v[46:49], v[52:55], v[0:15]
	v_cvt_pk_bf16_f32 v42, v98, v102
	v_cvt_pk_bf16_f32 v43, v99, v103
	v_cvt_pk_bf16_f32 v34, v100, v104
	v_cvt_pk_bf16_f32 v35, v101, v105
	v_add_f32_e32 v50, v50, v51
	v_fmac_f32_e32 v50, v94, v44
	v_mov_b32_e32 v94, v50
	s_waitcnt lgkmcnt(0)
	v_mfma_f32_32x32x16_bf16 v[16:31], v[56:59], v[52:55], v[16:31]
	ds_read_b128 v[46:49], v97 offset:18464
	ds_read_b128 v[52:55], v97 offset:23072
	v_mov_b32_e32 v98, v45
	s_waitcnt lgkmcnt(1)
	v_mfma_f32_32x32x16_bf16 v[0:15], v[46:49], v[40:43], v[0:15]
	s_waitcnt lgkmcnt(0)
	v_mfma_f32_32x32x16_bf16 v[16:31], v[52:55], v[40:43], v[16:31]
	ds_read_b128 v[40:43], v97 offset:18496
	ds_read_b128 v[46:49], v97 offset:23104
	s_waitcnt lgkmcnt(1)
	v_mfma_f32_32x32x16_bf16 v[0:15], v[40:43], v[36:39], v[0:15]
	s_waitcnt lgkmcnt(0)
	v_mfma_f32_32x32x16_bf16 v[16:31], v[46:49], v[36:39], v[16:31]
	ds_read_b128 v[36:39], v97 offset:18528
	ds_read_b128 v[40:43], v97 offset:23136
	s_waitcnt lgkmcnt(1)
	v_mfma_f32_32x32x16_bf16 v[0:15], v[36:39], v[32:35], v[0:15]
	s_waitcnt lgkmcnt(0)
	v_mfma_f32_32x32x16_bf16 v[16:31], v[40:43], v[32:35], v[16:31]
	s_branch .LBB0_264
